# gate pre-activation scaling folded into the staged conv taps (one multiply less per gate element in the up-GEMM epilogue); code layout shifted
# baseline (speedup 1.0000x reference)
; #define PG8_LAS __attribute__((address_space(3)))
; #define PG8_STAGE(bufoff, gbase, voff) do { _Pragma("unroll") for (int _i = 0; _i < 2; ++_i) \
;         __builtin_amdgcn_global_load_lds((const unsigned*)((const char*)(gbase) + (voff)[_i]), (PG8_LAS unsigned*)(lds + (bufoff) + ldsw + _i * 8192), 16, 0, 0); } while (0)
; #define PG8_WAIT_V(n) asm volatile("s_waitcnt vmcnt(" #n ")" ::: "memory")
; #define PG8_BAR __builtin_amdgcn_s_barrier()
; template <class Epi, class Sched, bool ALIGN_EPI = false, bool SP2 = false>
; __device__ __forceinline__ void gemm_phase(PG8_LAS unsigned char* lds, const Gemm g, const Sched& S, const Epi& E) {
;     ...
;         PG8_STAGE(PG8_SB(0, 0), cB, voffB); PG8_STAGE(PG8_SB(0, 1), cB + hstep, voffB); PG8_STAGE(PG8_SA(0, 0), cA, voffA); PG8_STAGE(PG8_SA(0, 1), cA + hstep, voffA);
;         if (wr == 1) PG8_BAR;
;         PG8_WAIT_V(2); PG8_BAR;
;         PG8_STAGE(PG8_SB(1, 0), cB + kstep, voffB); PG8_STAGE(PG8_SA(1, 0), cA + kstep, voffA); PG8_STAGE(PG8_SB(1, 1), cB + hstep + kstep, voffB);
;         PG8_WAIT_V(6); PG8_BAR;
;     } else {
;         PG8_STAGE(PG8_SB(0, 0), cB, voffB); PG8_STAGE(PG8_SA(0, 0), cA, voffA); PG8_STAGE(PG8_SB(0, 1), cB + hstep, voffB); PG8_STAGE(PG8_SA(0, 1), cA + hstep, voffA);
;         if (wr == 1) PG8_BAR;
;         PG8_WAIT_V(4); PG8_BAR;
;         PG8_STAGE(PG8_SB(1, 0), cB + kstep, voffB); PG8_STAGE(PG8_SA(1, 0), cA + kstep, voffA); PG8_STAGE(PG8_SB(1, 1), cB + hstep + kstep, voffB);
;         PG8_WAIT_V(6); PG8_BAR;
;     __device__ __forceinline__ void operator()(f32x4 (&acc)[2][2][4][2], const pg8::Unit& u, int wr, int wc, int fr, int fq) const {
;         const int colj = u.pn * 128 + wc * 32 + 8 * fq;
;         PG8_LAS unsigned char* wl = WL + (wr * 4 + wc) * 1024;
;         {
;             const int l = fq * 16 + fr, p = l >> 4, bj = (l >> 3) & 1, c4 = (l & 7) * 4;
;             const float* srcp = (p < 3 ? FW + p * NUP : FB) + bj * DFF + u.pn * 128 + wc * 32 + c4;
;             *(PG8_LAS f32x4*)(wl + l * 16) = *(const f32x4*)srcp;
.LBB0_739:
	s_add_u32 s28, s16, 0xa000000
	s_mov_b64 s[30:31], 0x80
	s_addc_u32 s29, s17, 0
	s_and_b32 s5, s5, 3
	s_add_i32 m0, s35, 0x18000
	v_lshl_add_u64 v[6:7], v[6:7], 0, s[30:31]
	s_sext_i32_i16 s66, s0
	s_lshl_b32 s0, s4, 13
	s_lshl_b32 s12, s5, 12
	s_waitcnt vmcnt(2)
	s_barrier
	global_load_lds_dwordx4 v[6:7], off
	v_lshl_add_u64 v[4:5], v[4:5], 0, s[30:31]
	s_add_i32 m0, s35, 0x1a000
	s_add_i32 s54, s35, 0x8000
	s_add_i32 s55, s35, 0xa000
	global_load_lds_dwordx4 v[4:5], off
	v_lshl_add_u64 v[0:1], v[0:1], 0, s[30:31]
	s_mov_b32 m0, s54
	s_add_u32 s6, s10, 0x40080
	global_load_lds_dwordx4 v[0:1], off
	v_lshl_add_u64 v[0:1], v[2:3], 0, s[30:31]
	s_mov_b32 m0, s55
	s_addc_u32 s7, s11, 0
	global_load_lds_dwordx4 v[0:1], off
	s_add_i32 m0, s35, 0x1c000
	v_lshl_add_u64 v[0:1], s[6:7], 0, v[132:133]
	global_load_lds_dwordx4 v[0:1], off
	v_lshl_add_u64 v[0:1], s[6:7], 0, v[128:129]
	s_add_i32 m0, s35, 0x1e000
	v_lshrrev_b32_e32 v14, 4, v152
	global_load_lds_dwordx4 v[0:1], off
	v_and_b32_e32 v169, 15, v152
	v_bfe_u32 v239, v152, 3, 1
	v_mul_u32_u24_e32 v239, 0x873823, v239
	v_sub_u32_e32 v239, 0xbfb8aa3b, v239
	v_and_b32_e32 v15, 3, v14
	v_lshlrev_b32_e32 v14, 4, v15
	s_waitcnt vmcnt(0)
	v_lshlrev_b32_e32 v18, 2, v169
	v_lshl_or_b32 v17, v169, 6, v14
	v_and_b32_e32 v19, 32, v18
	s_cmpk_lt_u32 s1, 0x100
	v_bitop3_b32 v4, v17, s0, v19 bitop3:0xde
	v_lshlrev_b32_e32 v0, 6, v152
	s_movk_i32 s0, 0x3c0
	v_lshlrev_b32_e32 v1, 2, v152
	s_cselect_b64 s[84:85], -1, 0
	s_lshl_b32 s24, s4, 12
	v_and_or_b32 v0, v0, s0, v14
	v_and_b32_e32 v1, 32, v1
	s_lshl_b32 s38, s5, 10
	v_lshl_or_b32 v187, s4, 6, v18
	s_lshl_b32 s57, s4, 2
	s_add_i32 s4, s24, 0
	v_bitop3_b32 v171, s12, v0, v1 bitop3:0xf6
	v_bfe_u32 v0, v152, 3, 1
	v_mul_u32_u24_e32 v1, 0x1600, v15
	s_add_i32 s4, s4, s38
	v_readlane_b32 s36, v253, 18
	v_mul_u32_u24_e32 v2, 0xb00, v0
	v_lshlrev_b32_e32 v0, 2, v1
	v_mov_b32_e32 v1, v133
	v_readlane_b32 s46, v253, 28
	v_readlane_b32 s47, v253, 29
	v_readlane_b32 s49, v253, 31
	v_readlane_b32 s48, v253, 30
	v_lshl_add_u64 v[0:1], s[46:47], 0, v[0:1]
	v_mov_b32_e32 v3, s49
	v_cmp_eq_u32_e32 vcc, 3, v15
	v_lshlrev_b32_e32 v2, 2, v2
	v_lshlrev_b32_e32 v5, 4, v169
	v_cndmask_b32_e32 v1, v1, v3, vcc
	v_mov_b32_e32 v3, s48
	v_cndmask_b32_e32 v0, v0, v3, vcc
	v_mov_b32_e32 v3, v133
	v_lshl_add_u64 v[0:1], v[0:1], 0, v[2:3]
	s_lshl_b32 s24, s5, 7
	v_lshl_add_u64 v[0:1], v[0:1], 0, s[24:25]
	v_and_b32_e32 v2, 0x70, v5
	v_lshl_add_u64 v[136:137], v[0:1], 0, v[2:3]
	v_add3_u32 v0, v13, v10, v12
	v_lshl_or_b32 v0, v0, 11, v8
	s_mov_b64 s[12:13], 0x40080
	v_add_u32_e32 v0, v0, v9
	v_mov_b32_e32 v1, v133
	v_lshl_add_u64 v[140:141], v[0:1], 0, s[12:13]
	v_add3_u32 v0, v11, v10, v12
	v_lshl_or_b32 v0, v0, 11, v8
	s_waitcnt vmcnt(6)
	s_add_i32 s4, s4, 0x20100
	v_add_u32_e32 v0, v0, v9
	v_lshlrev_b32_e32 v16, 3, v15
	v_lshlrev_b32_e32 v6, 5, v15
	v_cmp_eq_u32_e64 s[6:7], 0, v169
	v_readlane_b32 s38, v253, 20
	v_lshl_add_u32 v2, v15, 8, s4
	v_mov_b32_e32 v15, v133
	v_lshl_add_u64 v[142:143], v[0:1], 0, s[12:13]
	s_add_i32 s61, 0, 0x10000
	s_add_i32 s62, 0, 0x14000
	v_mbcnt_lo_u32_b32 v0, -1, 0
	v_lshl_or_b32 v186, s5, 5, v16
	s_movk_i32 s56, 0x1600
	v_cmp_ne_u32_e64 s[0:1], 0, v169
	v_cndmask_b32_e64 v188, 2, 0, s[6:7]
	v_cndmask_b32_e64 v189, 3, 1, s[6:7]
	s_add_i32 s58, s57, 8
	s_ashr_i32 s59, s80, 31
	s_mov_b32 s60, s80
	v_readlane_b32 s40, v253, 22
	v_readlane_b32 s42, v253, 24
	v_lshl_add_u64 v[138:139], s[20:21], 0, v[14:15]
	v_mov_b64_e32 v[144:145], 0xb00
	v_mov_b64_e32 v[146:147], 0xaff
	v_add_u32_e32 v190, s61, v171
	v_add_u32_e32 v191, s62, v171
	v_add_u32_e32 v192, 0, v4
	v_add_u32_e32 v193, v2, v5
	v_mbcnt_hi_u32_b32 v194, -1, v0
	s_mov_b32 s24, 0x3a800000
	s_mov_b32 s38, 0x358637bd
	s_mov_b32 s63, 0x800000
	s_movk_i32 s64, 0x2c00
	s_movk_i32 s65, 0x1000
	v_add_u32_e32 v195, s4, v6
	s_barrier
	v_readlane_b32 s37, v253, 19
	v_readlane_b32 s39, v253, 21
	v_readlane_b32 s41, v253, 23
	v_readlane_b32 s43, v253, 25
	v_readlane_b32 s44, v253, 26
	v_readlane_b32 s45, v253, 27
	v_readlane_b32 s50, v253, 32
	v_readlane_b32 s51, v253, 33
	s_branch .LBB0_742

; #define PG8_LAS __attribute__((address_space(3)))
; __device__ __forceinline__ float row_up1(float v) { return dpp_mov<0x111>(v); }
;     __device__ __forceinline__ void operator()(f32x4 (&acc)[2][2][4][2], const pg8::Unit& u, int wr, int wc, int fr, int fq) const {
;         const int colj = u.pn * 128 + wc * 32 + 8 * fq;
;         PG8_LAS unsigned char* wl = WL + (wr * 4 + wc) * 1024;
;         {
;             const int l = fq * 16 + fr, p = l >> 4, bj = (l >> 3) & 1, c4 = (l & 7) * 4;
;             const float* srcp = (p < 3 ? FW + p * NUP : FB) + bj * DFF + u.pn * 128 + wc * 32 + c4;
;             *(PG8_LAS f32x4*)(wl + l * 16) = *(const f32x4*)srcp;
;         }
; #pragma unroll
;         for (int ai = 0; ai < 2; ++ai) {
;             const int tb = u.pm * 256 + ai * 128 + wr * 64 + 4 * fr;
;             float rstd[4];
; #pragma unroll
;             for (int m = 0; m < 4; ++m) { const f32x4 sv = *(const f32x4*)(SS + (size_t)(tb + m) * 16 + 4 * fq); float s = (sv[0] + sv[1]) + (sv[2] + sv[3]); s += __shfl_xor(s, 16); s += __shfl_xor(s, 32);
;                 rstd[m] = rsqrtf(s * (1.0f / 1024.0f) + EPS); }
;             u32x2 pk[2][4];
; #pragma unroll
;             for (int n = 0; n < 2; ++n) {
;                 f32x4 g[4];
;                 {   const PG8_LAS unsigned char* wq = wl + (8 * fq + 4 * n) * 4;
;                     const f32x4 w0 = *(const PG8_LAS f32x4*)(wq), w1 = *(const PG8_LAS f32x4*)(wq + 256), w2 = *(const PG8_LAS f32x4*)(wq + 512), bb = *(const PG8_LAS f32x4*)(wq + 768);
;                     const f32x4 x0 = acc[ai][0][0][n] * rstd[0], x1 = acc[ai][0][1][n] * rstd[1], x2 = acc[ai][0][2][n] * rstd[2], x3 = acc[ai][0][3][n] * rstd[3];
;                     acc[ai][0][0][n] = x0; acc[ai][0][1][n] = x1; acc[ai][0][2][n] = x2; acc[ai][0][3][n] = x3;
;                     f32x4 p1, p2;
; #pragma unroll
;                     for (int c = 0; c < 4; ++c) { p1[c] = row_up1(x3[c]); p2[c] = row_up1(x2[c]); }
.LBB0_748:
	v_lshl_add_u32 v148, s34, 8, v187
	v_ashrrev_i32_e32 v149, 31, v148
	v_lshlrev_b64 v[150:151], 6, v[148:149]
	v_lshl_add_u64 v[154:155], v[138:139], 0, v[150:151]
	v_or_b32_e32 v150, 1, v148
	v_ashrrev_i32_e32 v151, 31, v150
	v_lshlrev_b64 v[156:157], 6, v[150:151]
	v_lshl_add_u64 v[156:157], v[138:139], 0, v[156:157]
	global_load_dwordx4 v[160:163], v[154:155], off
	global_load_dwordx4 v[164:167], v[156:157], off
	v_or_b32_e32 v154, 2, v148
	v_ashrrev_i32_e32 v155, 31, v154
	v_lshlrev_b64 v[156:157], 6, v[154:155]
	v_lshl_add_u64 v[156:157], v[138:139], 0, v[156:157]
	global_load_dwordx4 v[172:175], v[156:157], off
	v_or_b32_e32 v156, 3, v148
	v_ashrrev_i32_e32 v157, 31, v156
	v_lshlrev_b64 v[158:159], 6, v[156:157]
	v_lshl_add_u64 v[158:159], v[138:139], 0, v[158:159]
	global_load_dwordx4 v[176:179], v[158:159], off
	s_lshl_b32 s8, s66, 7
	s_ashr_i32 s9, s8, 31
	v_lshl_add_u64 v[158:159], s[8:9], 2, v[136:137]
	global_load_dwordx4 v[180:183], v[158:159], off
	v_and_b32_e32 v151, 64, v194
	v_xor_b32_e32 v149, 16, v194
	v_add_u32_e32 v151, 64, v151
	v_cmp_lt_i32_e32 vcc, v149, v151
	v_xor_b32_e32 v155, 32, v194
	v_mov_b64_e32 v[184:185], s[38:39]
	v_cndmask_b32_e32 v149, v194, v149, vcc
	v_lshlrev_b32_e32 v149, 2, v149
	v_cmp_lt_i32_e32 vcc, v155, v151
	v_or_b32_e32 v158, s8, v186
	v_ashrrev_i32_e32 v159, 31, v158
	v_cndmask_b32_e32 v151, v194, v155, vcc
	v_lshlrev_b32_e32 v151, 2, v151
	s_waitcnt vmcnt(0)
	v_mov_b32_e32 v196, v161
	v_mov_b32_e32 v197, v162
	v_mov_b32_e32 v161, v163
	v_mov_b32_e32 v162, v165
	v_mov_b32_e32 v163, v166
	v_mov_b32_e32 v165, v167
	v_mov_b32_e32 v166, v173
	v_mov_b32_e32 v167, v174
	v_mov_b32_e32 v173, v175
	v_pk_add_f32 v[160:161], v[196:197], v[160:161]
	v_pk_add_f32 v[162:163], v[162:163], v[164:165]
	v_mov_b32_e32 v174, v177
	v_mov_b32_e32 v175, v178
	v_mov_b32_e32 v177, v179
	v_pk_add_f32 v[166:167], v[166:167], v[172:173]
	v_pk_add_f32 v[172:173], v[174:175], v[176:177]
	v_mov_b32_e32 v165, v160
	v_mov_b32_e32 v164, v162
	v_mov_b32_e32 v160, v163
	v_mov_b32_e32 v162, v172
	v_mov_b32_e32 v163, v166
	v_mov_b32_e32 v166, v173
	v_pk_add_f32 v[160:161], v[164:165], v[160:161]
	v_pk_add_f32 v[162:163], v[162:163], v[166:167]
	ds_bpermute_b32 v165, v149, v161
	ds_bpermute_b32 v164, v149, v160
	ds_bpermute_b32 v167, v149, v163
	ds_bpermute_b32 v166, v149, v162
	v_mul_f32_e32 v180, v239, v180
	v_mul_f32_e32 v181, v239, v181
	v_mul_f32_e32 v182, v239, v182
	v_mul_f32_e32 v183, v239, v183
	ds_write_b128 v193, v[180:183]
	s_waitcnt lgkmcnt(3)
	v_pk_add_f32 v[172:173], v[160:161], v[164:165]
	ds_bpermute_b32 v197, v151, v173
	s_waitcnt lgkmcnt(2)
	v_pk_add_f32 v[174:175], v[162:163], v[166:167]
	ds_bpermute_b32 v196, v151, v172
	ds_bpermute_b32 v199, v151, v175
	ds_bpermute_b32 v198, v151, v174
	ds_read_b128 v[160:163], v195
	ds_read_b128 v[164:167], v195 offset:256
	ds_read_b128 v[176:179], v195 offset:512
	ds_read_b128 v[180:183], v195 offset:768
	s_waitcnt lgkmcnt(6)
	v_pk_add_f32 v[172:173], v[172:173], v[196:197]
	s_nop 0
	v_pk_fma_f32 v[172:173], v[172:173], s[24:25], v[184:185] op_sel_hi:[1,0,0]
	s_waitcnt lgkmcnt(4)
	v_pk_add_f32 v[174:175], v[174:175], v[198:199]
	v_mul_f32_e32 v155, 0x4b800000, v173
	v_pk_fma_f32 v[174:175], v[174:175], s[24:25], v[184:185] op_sel_hi:[1,0,0]
	v_cmp_gt_f32_e32 vcc, s63, v173
	v_mul_f32_e32 v168, 0x4b800000, v175
	v_mul_f32_e32 v170, 0x4b800000, v174
	v_cmp_gt_f32_e64 s[10:11], s63, v175
	v_cmp_gt_f32_e64 s[12:13], s63, v174
	v_cndmask_b32_e32 v155, v173, v155, vcc
	v_cndmask_b32_e64 v168, v175, v168, s[10:11]
	v_cndmask_b32_e64 v170, v174, v170, s[12:13]
	v_rsq_f32_e32 v155, v155
	v_rsq_f32_e32 v168, v168
	v_rsq_f32_e32 v173, v170
	v_mul_f32_e32 v157, 0x4b800000, v172
	v_cmp_gt_f32_e64 s[8:9], s63, v172
	v_mul_f32_e32 v170, 0x45800000, v155
	v_mul_f32_e32 v175, 0x45800000, v168
	v_cndmask_b32_e64 v157, v172, v157, s[8:9]
	v_mul_f32_e32 v184, 0x45800000, v173
	v_rsq_f32_e32 v157, v157
	v_cndmask_b32_e32 v174, v155, v170, vcc
	v_cndmask_b32_e64 v170, v168, v175, s[10:11]
	v_cndmask_b32_e64 v168, v173, v184, s[12:13]
	v_pk_mul_f32 v[124:125], v[124:125], v[174:175] op_sel_hi:[1,0]
	v_pk_mul_f32 v[112:113], v[112:113], v[168:169] op_sel_hi:[1,0]
	v_pk_mul_f32 v[116:117], v[116:117], v[170:171] op_sel_hi:[1,0]
	s_waitcnt lgkmcnt(0)
; #define PG8_LAS __attribute__((address_space(3)))
;     __device__ __forceinline__ void operator()(f32x4 (&acc)[2][2][4][2], const pg8::Unit& u, int wr, int wc, int fr, int fq) const {
;     ...
;             for (int n = 0; n < 2; ++n) {
;                 f32x4 g[4];
;                 {   const PG8_LAS unsigned char* wq = wl + (8 * fq + 4 * n) * 4;
;                     const f32x4 w0 = *(const PG8_LAS f32x4*)(wq), w1 = *(const PG8_LAS f32x4*)(wq + 256), w2 = *(const PG8_LAS f32x4*)(wq + 512), bb = *(const PG8_LAS f32x4*)(wq + 768);
;                     const f32x4 x0 = acc[ai][0][0][n] * rstd[0], x1 = acc[ai][0][1][n] * rstd[1], x2 = acc[ai][0][2][n] * rstd[2], x3 = acc[ai][0][3][n] * rstd[3];
;                     acc[ai][0][0][n] = x0; acc[ai][0][1][n] = x1; acc[ai][0][2][n] = x2; acc[ai][0][3][n] = x3;
;                     f32x4 p1, p2;
; #pragma unroll
;                     for (int c = 0; c < 4; ++c) { p1[c] = row_up1(x3[c]); p2[c] = row_up1(x2[c]); }
;                     g[0] = bb + w2 * x0 + w1 * p1 + w0 * p2; g[1] = bb + w2 * x1 + w1 * x0 + w0 * p1;
;                     g[2] = bb + w2 * x2 + w1 * x1 + w0 * x0; g[3] = bb + w2 * x3 + w1 * x2 + w0 * x1;
; #pragma unroll
;                     for (int m = 0; m < 4; ++m)
; #pragma unroll
;                         for (int c = 0; c < 4; ++c) g[m][c] = siluf_(g[m][c]);
;                 }
;                 __builtin_amdgcn_sched_barrier(0);
;                 {   const PG8_LAS unsigned char* wq = wl + 128 + (8 * fq + 4 * n) * 4;
;                     const f32x4 w0 = *(const PG8_LAS f32x4*)(wq), w1 = *(const PG8_LAS f32x4*)(wq + 256), w2 = *(const PG8_LAS f32x4*)(wq + 512), bb = *(const PG8_LAS f32x4*)(wq + 768);
;                     const f32x4 x0 = acc[ai][1][0][n] * rstd[0], x1 = acc[ai][1][1][n] * rstd[1], x2 = acc[ai][1][2][n] * rstd[2], x3 = acc[ai][1][3][n] * rstd[3];
;                     acc[ai][1][0][n] = x0; acc[ai][1][1][n] = x1; acc[ai][1][2][n] = x2; acc[ai][1][3][n] = x3;
;                     f32x4 p1, p2;
; #pragma unroll
;                     for (int c = 0; c < 4; ++c) { p1[c] = row_up1(x3[c]); p2[c] = row_up1(x2[c]); }
;                     g[0] *= bb + w2 * x0 + w1 * p1 + w0 * p2; g[1] *= bb + w2 * x1 + w1 * x0 + w0 * p1;
;                     g[2] *= bb + w2 * x2 + w1 * x1 + w0 * x0; g[3] *= bb + w2 * x3 + w1 * x2 + w0 * x1;
;                 }
; #pragma unroll
	v_pk_fma_f32 v[204:205], v[176:177], v[124:125], v[180:181]
	v_mov_b32_dpp v184, v112 row_shr:1 row_mask:0xf bank_mask:0xf bound_ctrl:1
	v_mov_b32_dpp v185, v113 row_shr:1 row_mask:0xf bank_mask:0xf bound_ctrl:1
	v_mov_b32_dpp v196, v116 row_shr:1 row_mask:0xf bank_mask:0xf bound_ctrl:1
	v_mov_b32_dpp v197, v117 row_shr:1 row_mask:0xf bank_mask:0xf bound_ctrl:1
	v_pk_fma_f32 v[204:205], v[164:165], v[184:185], v[204:205]
	v_mul_f32_e32 v172, 0x45800000, v157
	v_pk_fma_f32 v[196:197], v[160:161], v[196:197], v[204:205]
	v_cndmask_b32_e64 v172, v157, v172, s[8:9]
	v_pk_mul_f32 v[126:127], v[126:127], v[174:175] op_sel_hi:[1,0]
	v_pk_mul_f32 v[120:121], v[120:121], v[172:173] op_sel_hi:[1,0]
	v_pk_mul_f32 v[114:115], v[114:115], v[168:169] op_sel_hi:[1,0]
	v_exp_f32_e32 v155, v196
	v_pk_mul_f32 v[118:119], v[118:119], v[170:171] op_sel_hi:[1,0]
	v_mov_b32_dpp v198, v114 row_shr:1 row_mask:0xf bank_mask:0xf bound_ctrl:1
	v_mov_b32_dpp v199, v115 row_shr:1 row_mask:0xf bank_mask:0xf bound_ctrl:1
	v_pk_fma_f32 v[202:203], v[178:179], v[126:127], v[182:183]
	v_pk_fma_f32 v[204:205], v[176:177], v[120:121], v[180:181]
	v_exp_f32_e32 v157, v197
	v_pk_mul_f32 v[122:123], v[122:123], v[172:173] op_sel_hi:[1,0]
	v_mov_b32_dpp v200, v118 row_shr:1 row_mask:0xf bank_mask:0xf bound_ctrl:1
	v_mov_b32_dpp v201, v119 row_shr:1 row_mask:0xf bank_mask:0xf bound_ctrl:1
	v_pk_fma_f32 v[202:203], v[166:167], v[198:199], v[202:203]
	v_pk_fma_f32 v[204:205], v[164:165], v[124:125], v[204:205]
	v_pk_fma_f32 v[200:201], v[162:163], v[200:201], v[202:203]
	v_pk_fma_f32 v[202:203], v[178:179], v[122:123], v[182:183]
	v_pk_fma_f32 v[184:185], v[160:161], v[184:185], v[204:205]
	v_pk_fma_f32 v[204:205], v[176:177], v[116:117], v[180:181]
	v_pk_fma_f32 v[176:177], v[176:177], v[112:113], v[180:181]
	v_pk_fma_f32 v[202:203], v[166:167], v[126:127], v[202:203]
	v_pk_fma_f32 v[204:205], v[164:165], v[120:121], v[204:205]
	v_pk_fma_f32 v[164:165], v[164:165], v[116:117], v[176:177]
	v_add_f32_e32 v155, 1.0, v155
	v_pk_fma_f32 v[198:199], v[162:163], v[198:199], v[202:203]
	v_pk_fma_f32 v[202:203], v[178:179], v[118:119], v[182:183]
	v_pk_fma_f32 v[204:205], v[160:161], v[124:125], v[204:205]
	v_pk_fma_f32 v[178:179], v[178:179], v[114:115], v[182:183]
	v_pk_fma_f32 v[214:215], v[160:161], v[120:121], v[164:165]
	v_rcp_f32_e32 v160, v155
	v_add_f32_e32 v155, 1.0, v157
	v_pk_fma_f32 v[202:203], v[166:167], v[122:123], v[202:203]
	v_pk_fma_f32 v[166:167], v[166:167], v[118:119], v[178:179]
	v_exp_f32_e32 v157, v200
	v_pk_fma_f32 v[202:203], v[162:163], v[126:127], v[202:203]
	v_pk_fma_f32 v[212:213], v[162:163], v[122:123], v[166:167]
	v_exp_f32_e32 v163, v201
	v_rcp_f32_e32 v161, v155
	v_add_f32_e32 v155, 1.0, v157
	v_rcp_f32_e32 v162, v155
	v_add_f32_e32 v155, 1.0, v163
	v_rcp_f32_e32 v163, v155
	v_exp_f32_e32 v155, v184
	v_exp_f32_e32 v157, v185
	v_pk_mul_f32 v[216:217], v[196:197], v[160:161]
	v_add_f32_e32 v155, 1.0, v155
	v_rcp_f32_e32 v160, v155
	v_add_f32_e32 v155, 1.0, v157
	v_exp_f32_e32 v157, v198
	v_pk_mul_f32 v[218:219], v[200:201], v[162:163]
	v_exp_f32_e32 v163, v199
	v_rcp_f32_e32 v161, v155
	v_add_f32_e32 v155, 1.0, v157
	v_rcp_f32_e32 v162, v155
	v_add_f32_e32 v155, 1.0, v163
	v_rcp_f32_e32 v163, v155
	v_exp_f32_e32 v155, v204
	v_exp_f32_e32 v157, v205
	v_pk_mul_f32 v[184:185], v[184:185], v[160:161]
	v_add_f32_e32 v155, 1.0, v155
	v_rcp_f32_e32 v160, v155
	v_add_f32_e32 v155, 1.0, v157
	v_exp_f32_e32 v157, v202
	v_exp_f32_e32 v165, v203
	v_rcp_f32_e32 v161, v155
	v_add_f32_e32 v155, 1.0, v157
	v_rcp_f32_e32 v164, v155
	v_add_f32_e32 v155, 1.0, v165
	v_exp_f32_e32 v157, v214
	v_exp_f32_e32 v166, v215
	v_rcp_f32_e32 v165, v155
	v_add_f32_e32 v155, 1.0, v157
	v_rcp_f32_e32 v220, v155
	v_add_f32_e32 v155, 1.0, v166
	v_exp_f32_e32 v157, v212
	v_exp_f32_e32 v166, v213
	v_rcp_f32_e32 v221, v155
	v_add_f32_e32 v155, 1.0, v157
	v_rcp_f32_e32 v222, v155
	v_add_f32_e32 v155, 1.0, v166
	v_rcp_f32_e32 v223, v155
	v_pk_mul_f32 v[224:225], v[198:199], v[162:163]
	v_pk_mul_f32 v[226:227], v[204:205], v[160:161]
	v_pk_mul_f32 v[228:229], v[202:203], v[164:165]
	ds_read_b128 v[196:199], v195 offset:128
	ds_read_b128 v[200:203], v195 offset:384
	ds_read_b128 v[204:207], v195 offset:640
	ds_read_b128 v[208:211], v195 offset:896
	v_pk_mul_f32 v[176:177], v[108:109], v[174:175] op_sel_hi:[1,0]
	v_pk_mul_f32 v[164:165], v[96:97], v[168:169] op_sel_hi:[1,0]
	v_pk_mul_f32 v[180:181], v[100:101], v[170:171] op_sel_hi:[1,0]
	v_pk_mul_f32 v[160:161], v[104:105], v[172:173] op_sel_hi:[1,0]
	v_mov_b32_dpp v96, v164 row_shr:1 row_mask:0xf bank_mask:0xf bound_ctrl:1
	v_mov_b32_dpp v97, v165 row_shr:1 row_mask:0xf bank_mask:0xf bound_ctrl:1
	s_waitcnt lgkmcnt(0)
; #define PG8_LAS __attribute__((address_space(3)))
; __device__ __forceinline__ unsigned pk2(float a, float b) { return pg8::cvt_pk_bf16(a, b); }
; __device__ __forceinline__ float row_up1(float v) { return dpp_mov<0x111>(v); }
; __device__ __forceinline__ float siluf_(float x) { return x * __builtin_amdgcn_rcpf(1.0f + __builtin_amdgcn_exp2f(x * -1.4426950408889634f)); }
;     __device__ __forceinline__ void operator()(f32x4 (&acc)[2][2][4][2], const pg8::Unit& u, int wr, int wc, int fr, int fq) const {
;     ...
;                     g[0] = bb + w2 * x0 + w1 * p1 + w0 * p2; g[1] = bb + w2 * x1 + w1 * x0 + w0 * p1;
;                     g[2] = bb + w2 * x2 + w1 * x1 + w0 * x0; g[3] = bb + w2 * x3 + w1 * x2 + w0 * x1;
; #pragma unroll
;                     for (int m = 0; m < 4; ++m)
; #pragma unroll
;                         for (int c = 0; c < 4; ++c) g[m][c] = siluf_(g[m][c]);
;                 }
;                 __builtin_amdgcn_sched_barrier(0);
;                 {   const PG8_LAS unsigned char* wq = wl + 128 + (8 * fq + 4 * n) * 4;
;                     const f32x4 w0 = *(const PG8_LAS f32x4*)(wq), w1 = *(const PG8_LAS f32x4*)(wq + 256), w2 = *(const PG8_LAS f32x4*)(wq + 512), bb = *(const PG8_LAS f32x4*)(wq + 768);
;                     const f32x4 x0 = acc[ai][1][0][n] * rstd[0], x1 = acc[ai][1][1][n] * rstd[1], x2 = acc[ai][1][2][n] * rstd[2], x3 = acc[ai][1][3][n] * rstd[3];
;                     acc[ai][1][0][n] = x0; acc[ai][1][1][n] = x1; acc[ai][1][2][n] = x2; acc[ai][1][3][n] = x3;
;                     f32x4 p1, p2;
; #pragma unroll
;                     for (int c = 0; c < 4; ++c) { p1[c] = row_up1(x3[c]); p2[c] = row_up1(x2[c]); }
;                     g[0] *= bb + w2 * x0 + w1 * p1 + w0 * p2; g[1] *= bb + w2 * x1 + w1 * x0 + w0 * p1;
;                     g[2] *= bb + w2 * x2 + w1 * x1 + w0 * x0; g[3] *= bb + w2 * x3 + w1 * x2 + w0 * x1;
;                 }
; #pragma unroll
;                 for (int m = 0; m < 4; ++m) { pk[n][m].x = pk2(g[m][0], g[m][1]); pk[n][m].y = pk2(g[m][2], g[m][3]); }
	v_pk_fma_f32 v[108:109], v[176:177], v[204:205], v[208:209]
	v_pk_mul_f32 v[166:167], v[98:99], v[168:169] op_sel_hi:[1,0]
	v_mov_b32_dpp v98, v180 row_shr:1 row_mask:0xf bank_mask:0xf bound_ctrl:1
	v_mov_b32_dpp v99, v181 row_shr:1 row_mask:0xf bank_mask:0xf bound_ctrl:1
	v_pk_fma_f32 v[108:109], v[200:201], v[96:97], v[108:109]
	v_pk_mul_f32 v[178:179], v[110:111], v[174:175] op_sel_hi:[1,0]
	v_pk_fma_f32 v[98:99], v[196:197], v[98:99], v[108:109]
	v_pk_fma_f32 v[108:109], v[160:161], v[204:205], v[208:209]
	v_pk_mul_f32 v[182:183], v[102:103], v[170:171] op_sel_hi:[1,0]
	v_mov_b32_dpp v100, v166 row_shr:1 row_mask:0xf bank_mask:0xf bound_ctrl:1
	v_mov_b32_dpp v101, v167 row_shr:1 row_mask:0xf bank_mask:0xf bound_ctrl:1
	v_pk_fma_f32 v[110:111], v[178:179], v[206:207], v[210:211]
	v_pk_fma_f32 v[108:109], v[176:177], v[200:201], v[108:109]
	v_pk_mul_f32 v[162:163], v[106:107], v[172:173] op_sel_hi:[1,0]
	v_mov_b32_dpp v102, v182 row_shr:1 row_mask:0xf bank_mask:0xf bound_ctrl:1
	v_mov_b32_dpp v103, v183 row_shr:1 row_mask:0xf bank_mask:0xf bound_ctrl:1
	v_pk_fma_f32 v[110:111], v[202:203], v[100:101], v[110:111]
	v_pk_fma_f32 v[96:97], v[196:197], v[96:97], v[108:109]
	v_pk_fma_f32 v[108:109], v[180:181], v[204:205], v[208:209]
	v_pk_fma_f32 v[102:103], v[198:199], v[102:103], v[110:111]
	v_pk_fma_f32 v[110:111], v[162:163], v[206:207], v[210:211]
	v_pk_fma_f32 v[108:109], v[160:161], v[200:201], v[108:109]
	v_pk_fma_f32 v[110:111], v[178:179], v[202:203], v[110:111]
	v_pk_fma_f32 v[108:109], v[176:177], v[196:197], v[108:109]
	v_pk_fma_f32 v[100:101], v[198:199], v[100:101], v[110:111]
	v_pk_mul_f32 v[96:97], v[184:185], v[96:97]
	v_pk_fma_f32 v[110:111], v[182:183], v[206:207], v[210:211]
	v_pk_mul_f32 v[184:185], v[108:109], v[226:227]
	v_pk_fma_f32 v[108:109], v[164:165], v[204:205], v[208:209]
	v_pk_fma_f32 v[204:205], v[166:167], v[206:207], v[210:211]
	v_pk_fma_f32 v[110:111], v[162:163], v[202:203], v[110:111]
	v_pk_fma_f32 v[202:203], v[182:183], v[202:203], v[204:205]
	v_pk_fma_f32 v[108:109], v[180:181], v[200:201], v[108:109]
	v_pk_mul_f32 v[106:107], v[212:213], v[222:223]
	v_pk_fma_f32 v[110:111], v[178:179], v[198:199], v[110:111]
	v_pk_fma_f32 v[108:109], v[160:161], v[196:197], v[108:109]
	v_pk_fma_f32 v[196:197], v[162:163], v[198:199], v[202:203]
	v_pk_mul_f32 v[104:105], v[214:215], v[220:221]
	v_pk_mul_f32 v[102:103], v[218:219], v[102:103]
	v_pk_mul_f32 v[98:99], v[216:217], v[98:99]
	v_pk_mul_f32 v[100:101], v[224:225], v[100:101]
	v_pk_mul_f32 v[110:111], v[110:111], v[228:229]
	v_pk_mul_f32 v[106:107], v[196:197], v[106:107]
	v_pk_mul_f32 v[196:197], v[108:109], v[104:105]
	v_cvt_pk_bf16_f32 v108, v98, v99
	v_cvt_pk_bf16_f32 v109, v102, v103
	v_cvt_pk_bf16_f32 v104, v96, v97
	v_cvt_pk_bf16_f32 v105, v100, v101
	v_cvt_pk_bf16_f32 v100, v184, v185
	v_cvt_pk_bf16_f32 v101, v110, v111
	s_nop 0
	v_cvt_pk_bf16_f32 v96, v196, v197
	v_cvt_pk_bf16_f32 v97, v106, v107
	ds_read_b128 v[196:199], v195 offset:16
	ds_read_b128 v[200:203], v195 offset:272
	ds_read_b128 v[204:207], v195 offset:528
	ds_read_b128 v[208:211], v195 offset:784
	v_pk_mul_f32 v[92:93], v[92:93], v[174:175] op_sel_hi:[1,0]
	v_pk_mul_f32 v[84:85], v[84:85], v[168:169] op_sel_hi:[1,0]
	v_pk_mul_f32 v[88:89], v[88:89], v[170:171] op_sel_hi:[1,0]
	v_pk_mul_f32 v[80:81], v[80:81], v[172:173] op_sel_hi:[1,0]
	v_mov_b32_dpp v98, v84 row_shr:1 row_mask:0xf bank_mask:0xf bound_ctrl:1
	v_mov_b32_dpp v99, v85 row_shr:1 row_mask:0xf bank_mask:0xf bound_ctrl:1
	s_waitcnt lgkmcnt(0)
	v_pk_fma_f32 v[212:213], v[92:93], v[204:205], v[208:209]
	v_mov_b32_dpp v102, v88 row_shr:1 row_mask:0xf bank_mask:0xf bound_ctrl:1
	v_mov_b32_dpp v103, v89 row_shr:1 row_mask:0xf bank_mask:0xf bound_ctrl:1
	v_pk_fma_f32 v[212:213], v[200:201], v[98:99], v[212:213]
	v_pk_mul_f32 v[94:95], v[94:95], v[174:175] op_sel_hi:[1,0]
	v_pk_fma_f32 v[102:103], v[196:197], v[102:103], v[212:213]
	v_pk_mul_f32 v[86:87], v[86:87], v[168:169] op_sel_hi:[1,0]
	v_exp_f32_e32 v155, v102
	v_pk_fma_f32 v[212:213], v[80:81], v[204:205], v[208:209]
	v_exp_f32_e32 v157, v103
	v_pk_mul_f32 v[90:91], v[90:91], v[170:171] op_sel_hi:[1,0]
	v_mov_b32_dpp v106, v86 row_shr:1 row_mask:0xf bank_mask:0xf bound_ctrl:1
	v_mov_b32_dpp v107, v87 row_shr:1 row_mask:0xf bank_mask:0xf bound_ctrl:1
	v_pk_fma_f32 v[184:185], v[94:95], v[206:207], v[210:211]
	v_pk_fma_f32 v[212:213], v[92:93], v[200:201], v[212:213]
	v_mov_b32_dpp v110, v90 row_shr:1 row_mask:0xf bank_mask:0xf bound_ctrl:1
	v_mov_b32_dpp v111, v91 row_shr:1 row_mask:0xf bank_mask:0xf bound_ctrl:1
	v_pk_fma_f32 v[184:185], v[202:203], v[106:107], v[184:185]
	v_pk_fma_f32 v[98:99], v[196:197], v[98:99], v[212:213]
	v_pk_fma_f32 v[212:213], v[88:89], v[204:205], v[208:209]
	v_pk_fma_f32 v[204:205], v[84:85], v[204:205], v[208:209]
	v_pk_fma_f32 v[110:111], v[198:199], v[110:111], v[184:185]
	v_pk_fma_f32 v[212:213], v[80:81], v[200:201], v[212:213]
	v_pk_fma_f32 v[200:201], v[88:89], v[200:201], v[204:205]
	v_add_f32_e32 v155, 1.0, v155
	v_pk_fma_f32 v[212:213], v[92:93], v[196:197], v[212:213]
	v_pk_fma_f32 v[216:217], v[80:81], v[196:197], v[200:201]
	v_rcp_f32_e32 v196, v155
	v_add_f32_e32 v155, 1.0, v157
	v_pk_mul_f32 v[82:83], v[82:83], v[172:173] op_sel_hi:[1,0]
	v_exp_f32_e32 v157, v110
	v_pk_fma_f32 v[184:185], v[82:83], v[206:207], v[210:211]
	v_exp_f32_e32 v173, v111
	v_pk_fma_f32 v[184:185], v[94:95], v[202:203], v[184:185]
	v_rcp_f32_e32 v197, v155
	v_pk_fma_f32 v[106:107], v[198:199], v[106:107], v[184:185]
	v_pk_fma_f32 v[184:185], v[90:91], v[206:207], v[210:211]
; #define PG8_LAS __attribute__((address_space(3)))
; __device__ __forceinline__ unsigned pk2(float a, float b) { return pg8::cvt_pk_bf16(a, b); }
; __device__ __forceinline__ float row_up1(float v) { return dpp_mov<0x111>(v); }
;     __device__ __forceinline__ void operator()(f32x4 (&acc)[2][2][4][2], const pg8::Unit& u, int wr, int wc, int fr, int fq) const {
;     ...
;                 {   const PG8_LAS unsigned char* wq = wl + 128 + (8 * fq + 4 * n) * 4;
;                     const f32x4 w0 = *(const PG8_LAS f32x4*)(wq), w1 = *(const PG8_LAS f32x4*)(wq + 256), w2 = *(const PG8_LAS f32x4*)(wq + 512), bb = *(const PG8_LAS f32x4*)(wq + 768);
;                     const f32x4 x0 = acc[ai][1][0][n] * rstd[0], x1 = acc[ai][1][1][n] * rstd[1], x2 = acc[ai][1][2][n] * rstd[2], x3 = acc[ai][1][3][n] * rstd[3];
;                     acc[ai][1][0][n] = x0; acc[ai][1][1][n] = x1; acc[ai][1][2][n] = x2; acc[ai][1][3][n] = x3;
;                     f32x4 p1, p2;
; #pragma unroll
;                     for (int c = 0; c < 4; ++c) { p1[c] = row_up1(x3[c]); p2[c] = row_up1(x2[c]); }
;                     g[0] *= bb + w2 * x0 + w1 * p1 + w0 * p2; g[1] *= bb + w2 * x1 + w1 * x0 + w0 * p1;
;                     g[2] *= bb + w2 * x2 + w1 * x1 + w0 * x0; g[3] *= bb + w2 * x3 + w1 * x2 + w0 * x1;
;                 }
; #pragma unroll
;                 for (int m = 0; m < 4; ++m) { pk[n][m].x = pk2(g[m][0], g[m][1]); pk[n][m].y = pk2(g[m][2], g[m][3]); }
;                 __builtin_amdgcn_sched_barrier(0);
;             }
; #pragma unroll
;             for (int m = 0; m < 4; ++m) if (fr != 0 || m >= 2) {
;                 u32x4 w; w.x = pk[0][m].x; w.y = pk[0][m].y; w.z = pk[1][m].x; w.w = pk[1][m].y;
;                 *(u32x4*)(ACT + (size_t)(tb + m) * DFF + colj) = w; }
	v_pk_fma_f32 v[206:207], v[86:87], v[206:207], v[210:211]
	v_pk_fma_f32 v[184:185], v[82:83], v[202:203], v[184:185]
	v_pk_fma_f32 v[202:203], v[90:91], v[202:203], v[206:207]
	v_add_f32_e32 v155, 1.0, v157
	v_pk_fma_f32 v[184:185], v[94:95], v[198:199], v[184:185]
	v_pk_fma_f32 v[214:215], v[82:83], v[198:199], v[202:203]
	v_rcp_f32_e32 v198, v155
	v_add_f32_e32 v155, 1.0, v173
	v_rcp_f32_e32 v199, v155
	v_exp_f32_e32 v155, v98
	v_exp_f32_e32 v157, v99
	v_pk_mul_f32 v[102:103], v[102:103], v[196:197]
	v_add_f32_e32 v155, 1.0, v155
	v_rcp_f32_e32 v196, v155
	v_add_f32_e32 v155, 1.0, v157
	v_exp_f32_e32 v157, v106
	v_exp_f32_e32 v173, v107
	v_rcp_f32_e32 v197, v155
	v_add_f32_e32 v155, 1.0, v157
	v_pk_mul_f32 v[110:111], v[110:111], v[198:199]
	v_rcp_f32_e32 v198, v155
	v_add_f32_e32 v155, 1.0, v173
	v_rcp_f32_e32 v199, v155
	v_exp_f32_e32 v155, v212
	v_exp_f32_e32 v157, v213
	v_pk_mul_f32 v[98:99], v[98:99], v[196:197]
	v_add_f32_e32 v155, 1.0, v155
	v_rcp_f32_e32 v196, v155
	v_add_f32_e32 v155, 1.0, v157
	v_exp_f32_e32 v157, v184
	v_exp_f32_e32 v173, v185
	v_rcp_f32_e32 v197, v155
	v_add_f32_e32 v155, 1.0, v157
	v_rcp_f32_e32 v200, v155
	v_add_f32_e32 v155, 1.0, v173
	v_exp_f32_e32 v157, v216
	v_exp_f32_e32 v173, v217
	v_rcp_f32_e32 v201, v155
	v_add_f32_e32 v155, 1.0, v157
	v_rcp_f32_e32 v218, v155
	v_add_f32_e32 v155, 1.0, v173
	v_exp_f32_e32 v157, v214
	v_exp_f32_e32 v173, v215
	v_rcp_f32_e32 v219, v155
	v_add_f32_e32 v155, 1.0, v157
	v_rcp_f32_e32 v220, v155
	v_add_f32_e32 v155, 1.0, v173
	v_pk_mul_f32 v[106:107], v[106:107], v[198:199]
	v_rcp_f32_e32 v221, v155
	v_pk_mul_f32 v[212:213], v[212:213], v[196:197]
	v_pk_mul_f32 v[222:223], v[184:185], v[200:201]
	ds_read_b128 v[196:199], v195 offset:144
	ds_read_b128 v[200:203], v195 offset:400
	ds_read_b128 v[204:207], v195 offset:656
	ds_read_b128 v[208:211], v195 offset:912
	v_pk_mul_f32 v[184:185], v[66:67], v[174:175] op_sel_hi:[1,0]
	v_pk_mul_f32 v[174:175], v[64:65], v[174:175] op_sel_hi:[1,0]
	v_pk_mul_f32 v[66:67], v[68:69], v[172:173] op_sel_hi:[1,0]
	v_pk_mul_f32 v[68:69], v[76:77], v[168:169] op_sel_hi:[1,0]
	v_pk_mul_f32 v[70:71], v[70:71], v[172:173] op_sel_hi:[1,0]
	v_pk_mul_f32 v[172:173], v[74:75], v[170:171] op_sel_hi:[1,0]
	v_pk_mul_f32 v[74:75], v[72:73], v[170:171] op_sel_hi:[1,0]
	v_mov_b32_dpp v64, v68 row_shr:1 row_mask:0xf bank_mask:0xf bound_ctrl:1
	v_mov_b32_dpp v65, v69 row_shr:1 row_mask:0xf bank_mask:0xf bound_ctrl:1
	v_pk_mul_f32 v[216:217], v[216:217], v[218:219]
	s_waitcnt lgkmcnt(0)
	v_pk_fma_f32 v[218:219], v[174:175], v[204:205], v[208:209]
	v_pk_mul_f32 v[72:73], v[78:79], v[168:169] op_sel_hi:[1,0]
	v_mov_b32_dpp v76, v74 row_shr:1 row_mask:0xf bank_mask:0xf bound_ctrl:1
	v_mov_b32_dpp v77, v75 row_shr:1 row_mask:0xf bank_mask:0xf bound_ctrl:1
	v_pk_fma_f32 v[218:219], v[200:201], v[64:65], v[218:219]
	v_mov_b32_dpp v78, v72 row_shr:1 row_mask:0xf bank_mask:0xf bound_ctrl:1
	v_mov_b32_dpp v79, v73 row_shr:1 row_mask:0xf bank_mask:0xf bound_ctrl:1
	v_pk_mul_f32 v[214:215], v[214:215], v[220:221]
	v_pk_fma_f32 v[220:221], v[184:185], v[206:207], v[210:211]
	v_pk_fma_f32 v[76:77], v[196:197], v[76:77], v[218:219]
	v_mov_b32_dpp v224, v172 row_shr:1 row_mask:0xf bank_mask:0xf bound_ctrl:1
	v_mov_b32_dpp v225, v173 row_shr:1 row_mask:0xf bank_mask:0xf bound_ctrl:1
	v_pk_fma_f32 v[220:221], v[202:203], v[78:79], v[220:221]
	v_pk_mul_f32 v[76:77], v[102:103], v[76:77]
	v_pk_fma_f32 v[102:103], v[66:67], v[204:205], v[208:209]
	v_pk_fma_f32 v[218:219], v[198:199], v[224:225], v[220:221]
	v_pk_fma_f32 v[102:103], v[174:175], v[200:201], v[102:103]
	v_pk_mul_f32 v[218:219], v[110:111], v[218:219]
	v_pk_fma_f32 v[110:111], v[70:71], v[206:207], v[210:211]
	v_pk_fma_f32 v[64:65], v[196:197], v[64:65], v[102:103]
	v_pk_fma_f32 v[102:103], v[172:173], v[206:207], v[210:211]
	v_pk_fma_f32 v[110:111], v[184:185], v[202:203], v[110:111]
	v_pk_fma_f32 v[102:103], v[70:71], v[202:203], v[102:103]
	v_pk_fma_f32 v[78:79], v[198:199], v[78:79], v[110:111]
	v_pk_mul_f32 v[64:65], v[98:99], v[64:65]
	v_pk_fma_f32 v[98:99], v[74:75], v[204:205], v[208:209]
	v_pk_fma_f32 v[102:103], v[184:185], v[198:199], v[102:103]
	v_pk_mul_f32 v[78:79], v[106:107], v[78:79]
	v_pk_fma_f32 v[98:99], v[66:67], v[200:201], v[98:99]
	v_pk_mul_f32 v[220:221], v[222:223], v[102:103]
	v_pk_fma_f32 v[102:103], v[68:69], v[204:205], v[208:209]
	v_pk_fma_f32 v[106:107], v[72:73], v[206:207], v[210:211]
	v_pk_fma_f32 v[98:99], v[174:175], v[196:197], v[98:99]
	v_pk_fma_f32 v[106:107], v[172:173], v[202:203], v[106:107]
	v_pk_fma_f32 v[102:103], v[74:75], v[200:201], v[102:103]
	v_pk_mul_f32 v[98:99], v[212:213], v[98:99]
	v_pk_fma_f32 v[102:103], v[66:67], v[196:197], v[102:103]
	v_pk_fma_f32 v[106:107], v[70:71], v[198:199], v[106:107]
	v_pk_mul_f32 v[198:199], v[216:217], v[102:103]
	v_pk_mul_f32 v[196:197], v[214:215], v[106:107]
	v_cvt_pk_bf16_f32 v110, v76, v77
	v_cvt_pk_bf16_f32 v111, v218, v219
	v_cvt_pk_bf16_f32 v106, v64, v65
	v_cvt_pk_bf16_f32 v107, v78, v79
	v_cvt_pk_bf16_f32 v102, v98, v99
	v_cvt_pk_bf16_f32 v103, v220, v221
	v_cvt_pk_bf16_f32 v98, v198, v199
	s_nop 0
	v_cvt_pk_bf16_f32 v99, v196, v197
	v_lshlrev_b64 v[64:65], 1, v[158:159]
	s_and_saveexec_b64 s[8:9], s[0:1]
	s_cbranch_execz .LBB0_750
	v_mov_b64_e32 v[76:77], s[22:23]
	v_mad_i64_i32 v[78:79], s[10:11], v148, s56, v[76:77]
	v_mad_i64_i32 v[76:77], s[10:11], v150, s56, v[76:77]
	v_lshl_add_u64 v[78:79], v[78:79], 0, v[64:65]
	v_lshl_add_u64 v[76:77], v[76:77], 0, v[64:65]
	global_store_dwordx4 v[78:79], v[108:111], off
	global_store_dwordx4 v[76:77], v[104:107], off

; #define PG8_LAS __attribute__((address_space(3)))
; __device__ __forceinline__ float row_up1(float v) { return dpp_mov<0x111>(v); }
;     __device__ __forceinline__ void operator()(f32x4 (&acc)[2][2][4][2], const pg8::Unit& u, int wr, int wc, int fr, int fq) const {
;     ...
;         for (int ai = 0; ai < 2; ++ai) {
;             const int tb = u.pm * 256 + ai * 128 + wr * 64 + 4 * fr;
;             float rstd[4];
; #pragma unroll
;             for (int m = 0; m < 4; ++m) { const f32x4 sv = *(const f32x4*)(SS + (size_t)(tb + m) * 16 + 4 * fq); float s = (sv[0] + sv[1]) + (sv[2] + sv[3]); s += __shfl_xor(s, 16); s += __shfl_xor(s, 32);
;                 rstd[m] = rsqrtf(s * (1.0f / 1024.0f) + EPS); }
;             u32x2 pk[2][4];
; #pragma unroll
;             for (int n = 0; n < 2; ++n) {
;                 f32x4 g[4];
;                 {   const PG8_LAS unsigned char* wq = wl + (8 * fq + 4 * n) * 4;
;                     const f32x4 w0 = *(const PG8_LAS f32x4*)(wq), w1 = *(const PG8_LAS f32x4*)(wq + 256), w2 = *(const PG8_LAS f32x4*)(wq + 512), bb = *(const PG8_LAS f32x4*)(wq + 768);
;                     const f32x4 x0 = acc[ai][0][0][n] * rstd[0], x1 = acc[ai][0][1][n] * rstd[1], x2 = acc[ai][0][2][n] * rstd[2], x3 = acc[ai][0][3][n] * rstd[3];
;                     acc[ai][0][0][n] = x0; acc[ai][0][1][n] = x1; acc[ai][0][2][n] = x2; acc[ai][0][3][n] = x3;
;                     f32x4 p1, p2;
; #pragma unroll
;                     for (int c = 0; c < 4; ++c) { p1[c] = row_up1(x3[c]); p2[c] = row_up1(x2[c]); }
;                     g[0] = bb + w2 * x0 + w1 * p1 + w0 * p2; g[1] = bb + w2 * x1 + w1 * x0 + w0 * p1;
.LBB0_754:
	s_or_b64 exec, exec, s[8:9]
	s_nop 0
	v_add_u32_e32 v66, 0x80, v148
	v_ashrrev_i32_e32 v67, 31, v66
	v_lshlrev_b64 v[68:69], 6, v[66:67]
	v_lshl_add_u64 v[70:71], v[138:139], 0, v[68:69]
	v_add_u32_e32 v68, 0x81, v148
	v_ashrrev_i32_e32 v69, 31, v68
	v_lshlrev_b64 v[72:73], 6, v[68:69]
	v_lshl_add_u64 v[72:73], v[138:139], 0, v[72:73]
	global_load_dwordx4 v[74:77], v[70:71], off
	global_load_dwordx4 v[78:81], v[72:73], off
	v_add_u32_e32 v70, 0x82, v148
	v_ashrrev_i32_e32 v71, 31, v70
	v_lshlrev_b64 v[72:73], 6, v[70:71]
	v_lshl_add_u64 v[72:73], v[138:139], 0, v[72:73]
	global_load_dwordx4 v[82:85], v[72:73], off
	v_add_u32_e32 v72, 0x83, v148
	v_ashrrev_i32_e32 v73, 31, v72
	v_lshlrev_b64 v[86:87], 6, v[72:73]
	v_lshl_add_u64 v[86:87], v[138:139], 0, v[86:87]
	global_load_dwordx4 v[86:89], v[86:87], off
	s_waitcnt vmcnt(3)
	v_mov_b32_e32 v90, v75
	v_mov_b32_e32 v91, v76
	v_mov_b32_e32 v75, v77
	s_waitcnt vmcnt(2)
	v_mov_b32_e32 v76, v79
	v_mov_b32_e32 v77, v80
	v_mov_b32_e32 v79, v81
	s_waitcnt vmcnt(1)
	v_mov_b32_e32 v80, v83
	v_mov_b32_e32 v81, v84
	v_mov_b32_e32 v83, v85
	v_pk_add_f32 v[74:75], v[90:91], v[74:75]
	v_pk_add_f32 v[76:77], v[76:77], v[78:79]
	s_waitcnt vmcnt(0)
	v_mov_b32_e32 v84, v87
	v_mov_b32_e32 v85, v88
	v_mov_b32_e32 v87, v89
	v_pk_add_f32 v[78:79], v[80:81], v[82:83]
	v_pk_add_f32 v[80:81], v[84:85], v[86:87]
	v_mov_b32_e32 v82, v76
	v_mov_b32_e32 v83, v74
	v_mov_b32_e32 v74, v77
	v_mov_b32_e32 v76, v80
	v_mov_b32_e32 v77, v78
	v_mov_b32_e32 v78, v81
	v_pk_add_f32 v[74:75], v[82:83], v[74:75]
	v_pk_add_f32 v[76:77], v[76:77], v[78:79]
	ds_bpermute_b32 v79, v149, v75
	ds_bpermute_b32 v78, v149, v74
	ds_bpermute_b32 v81, v149, v77
	ds_bpermute_b32 v80, v149, v76
	v_mov_b64_e32 v[82:83], s[38:39]
	s_waitcnt lgkmcnt(2)
	v_pk_add_f32 v[84:85], v[74:75], v[78:79]
	ds_bpermute_b32 v89, v151, v85
	s_waitcnt lgkmcnt(1)
	v_pk_add_f32 v[86:87], v[76:77], v[80:81]
	ds_bpermute_b32 v88, v151, v84
	ds_bpermute_b32 v99, v151, v87
	ds_bpermute_b32 v98, v151, v86
	ds_read_b128 v[74:77], v195
	ds_read_b128 v[78:81], v195 offset:256
	ds_read_b128 v[90:93], v195 offset:512
	ds_read_b128 v[94:97], v195 offset:768
	s_waitcnt lgkmcnt(6)
	v_pk_add_f32 v[84:85], v[84:85], v[88:89]
	s_nop 0
	v_pk_fma_f32 v[84:85], v[84:85], s[24:25], v[82:83] op_sel_hi:[1,0,0]
	s_waitcnt lgkmcnt(4)
	v_pk_add_f32 v[86:87], v[86:87], v[98:99]
	v_mul_f32_e32 v67, 0x4b800000, v85
	v_pk_fma_f32 v[82:83], v[86:87], s[24:25], v[82:83] op_sel_hi:[1,0,0]
	v_cmp_gt_f32_e32 vcc, s63, v85
	v_mul_f32_e32 v73, 0x4b800000, v82
	v_cmp_gt_f32_e64 s[12:13], s63, v82
	v_mul_f32_e32 v69, 0x4b800000, v84
	v_mul_f32_e32 v71, 0x4b800000, v83
	v_cndmask_b32_e32 v67, v85, v67, vcc
	v_cmp_gt_f32_e64 s[8:9], s63, v84
	v_cmp_gt_f32_e64 s[10:11], s63, v83
	v_cndmask_b32_e64 v73, v82, v73, s[12:13]
	v_cndmask_b32_e64 v69, v84, v69, s[8:9]
	v_cndmask_b32_e64 v71, v83, v71, s[10:11]
	v_rsq_f32_e32 v67, v67
	v_rsq_f32_e32 v73, v73
	v_rsq_f32_e32 v69, v69
	v_rsq_f32_e32 v71, v71
	v_mul_f32_e32 v82, 0x45800000, v67
	v_mul_f32_e32 v85, 0x45800000, v73
	v_mul_f32_e32 v83, 0x45800000, v69
	v_mul_f32_e32 v84, 0x45800000, v71
	v_cndmask_b32_e32 v88, v67, v82, vcc
	v_cndmask_b32_e64 v82, v73, v85, s[12:13]
	v_cndmask_b32_e64 v84, v71, v84, s[10:11]
	v_pk_mul_f32 v[60:61], v[60:61], v[88:89] op_sel_hi:[1,0]
	v_pk_mul_f32 v[48:49], v[48:49], v[82:83] op_sel_hi:[1,0]
	v_pk_mul_f32 v[52:53], v[52:53], v[84:85] op_sel_hi:[1,0]
	s_waitcnt lgkmcnt(0)
	v_pk_fma_f32 v[108:109], v[90:91], v[60:61], v[94:95]
	v_mov_b32_dpp v98, v48 row_shr:1 row_mask:0xf bank_mask:0xf bound_ctrl:1
	v_mov_b32_dpp v99, v49 row_shr:1 row_mask:0xf bank_mask:0xf bound_ctrl:1
	v_mov_b32_dpp v100, v52 row_shr:1 row_mask:0xf bank_mask:0xf bound_ctrl:1
	v_mov_b32_dpp v101, v53 row_shr:1 row_mask:0xf bank_mask:0xf bound_ctrl:1
	v_pk_fma_f32 v[108:109], v[78:79], v[98:99], v[108:109]
	v_cndmask_b32_e64 v86, v69, v83, s[8:9]
	v_pk_fma_f32 v[100:101], v[74:75], v[100:101], v[108:109]
	v_pk_mul_f32 v[62:63], v[62:63], v[88:89] op_sel_hi:[1,0]
	v_exp_f32_e32 v67, v100
	v_pk_mul_f32 v[50:51], v[50:51], v[82:83] op_sel_hi:[1,0]
	v_exp_f32_e32 v69, v101
	v_pk_mul_f32 v[56:57], v[56:57], v[86:87] op_sel_hi:[1,0]
	v_pk_mul_f32 v[54:55], v[54:55], v[84:85] op_sel_hi:[1,0]
	v_mov_b32_dpp v102, v50 row_shr:1 row_mask:0xf bank_mask:0xf bound_ctrl:1
	v_mov_b32_dpp v103, v51 row_shr:1 row_mask:0xf bank_mask:0xf bound_ctrl:1
	v_pk_fma_f32 v[106:107], v[92:93], v[62:63], v[96:97]
	v_mov_b32_dpp v104, v54 row_shr:1 row_mask:0xf bank_mask:0xf bound_ctrl:1
	v_mov_b32_dpp v105, v55 row_shr:1 row_mask:0xf bank_mask:0xf bound_ctrl:1
	v_pk_fma_f32 v[112:113], v[90:91], v[56:57], v[94:95]
	v_pk_fma_f32 v[106:107], v[80:81], v[102:103], v[106:107]
	v_pk_fma_f32 v[108:109], v[90:91], v[52:53], v[94:95]
	v_pk_fma_f32 v[90:91], v[90:91], v[48:49], v[94:95]
	v_pk_fma_f32 v[112:113], v[78:79], v[60:61], v[112:113]
	v_pk_fma_f32 v[104:105], v[76:77], v[104:105], v[106:107]
	v_pk_fma_f32 v[108:109], v[78:79], v[56:57], v[108:109]
	v_pk_fma_f32 v[78:79], v[78:79], v[52:53], v[90:91]
	v_add_f32_e32 v67, 1.0, v67
	v_pk_fma_f32 v[98:99], v[74:75], v[98:99], v[112:113]
	v_pk_fma_f32 v[108:109], v[74:75], v[60:61], v[108:109]
	v_pk_fma_f32 v[116:117], v[74:75], v[56:57], v[78:79]
	v_rcp_f32_e32 v74, v67
	v_add_f32_e32 v67, 1.0, v69
	v_exp_f32_e32 v69, v104
	v_exp_f32_e32 v71, v105
	v_pk_mul_f32 v[58:59], v[58:59], v[86:87] op_sel_hi:[1,0]
	v_pk_fma_f32 v[106:107], v[92:93], v[54:55], v[96:97]
	v_pk_fma_f32 v[110:111], v[92:93], v[58:59], v[96:97]
	v_pk_fma_f32 v[92:93], v[92:93], v[50:51], v[96:97]
	v_pk_fma_f32 v[110:111], v[80:81], v[62:63], v[110:111]
; #define PG8_LAS __attribute__((address_space(3)))
; __device__ __forceinline__ float row_up1(float v) { return dpp_mov<0x111>(v); }
; __device__ __forceinline__ float siluf_(float x) { return x * __builtin_amdgcn_rcpf(1.0f + __builtin_amdgcn_exp2f(x * -1.4426950408889634f)); }
;     __device__ __forceinline__ void operator()(f32x4 (&acc)[2][2][4][2], const pg8::Unit& u, int wr, int wc, int fr, int fq) const {
;     ...
;                     g[0] = bb + w2 * x0 + w1 * p1 + w0 * p2; g[1] = bb + w2 * x1 + w1 * x0 + w0 * p1;
;                     g[2] = bb + w2 * x2 + w1 * x1 + w0 * x0; g[3] = bb + w2 * x3 + w1 * x2 + w0 * x1;
; #pragma unroll
;                     for (int m = 0; m < 4; ++m)
; #pragma unroll
;                         for (int c = 0; c < 4; ++c) g[m][c] = siluf_(g[m][c]);
;                 }
;                 __builtin_amdgcn_sched_barrier(0);
;                 {   const PG8_LAS unsigned char* wq = wl + 128 + (8 * fq + 4 * n) * 4;
;                     const f32x4 w0 = *(const PG8_LAS f32x4*)(wq), w1 = *(const PG8_LAS f32x4*)(wq + 256), w2 = *(const PG8_LAS f32x4*)(wq + 512), bb = *(const PG8_LAS f32x4*)(wq + 768);
;                     const f32x4 x0 = acc[ai][1][0][n] * rstd[0], x1 = acc[ai][1][1][n] * rstd[1], x2 = acc[ai][1][2][n] * rstd[2], x3 = acc[ai][1][3][n] * rstd[3];
;                     acc[ai][1][0][n] = x0; acc[ai][1][1][n] = x1; acc[ai][1][2][n] = x2; acc[ai][1][3][n] = x3;
;                     f32x4 p1, p2;
; #pragma unroll
;                     for (int c = 0; c < 4; ++c) { p1[c] = row_up1(x3[c]); p2[c] = row_up1(x2[c]); }
;                     g[0] *= bb + w2 * x0 + w1 * p1 + w0 * p2; g[1] *= bb + w2 * x1 + w1 * x0 + w0 * p1;
;                     g[2] *= bb + w2 * x2 + w1 * x1 + w0 * x0; g[3] *= bb + w2 * x3 + w1 * x2 + w0 * x1;
	v_pk_fma_f32 v[106:107], v[80:81], v[58:59], v[106:107]
	v_pk_fma_f32 v[80:81], v[80:81], v[54:55], v[92:93]
	v_rcp_f32_e32 v75, v67
	v_add_f32_e32 v67, 1.0, v69
	v_pk_fma_f32 v[102:103], v[76:77], v[102:103], v[110:111]
	v_pk_fma_f32 v[106:107], v[76:77], v[62:63], v[106:107]
	v_pk_fma_f32 v[114:115], v[76:77], v[58:59], v[80:81]
	v_rcp_f32_e32 v76, v67
	v_add_f32_e32 v67, 1.0, v71
	v_rcp_f32_e32 v77, v67
	v_exp_f32_e32 v67, v98
	v_exp_f32_e32 v69, v99
	v_pk_mul_f32 v[118:119], v[100:101], v[74:75]
	v_add_f32_e32 v67, 1.0, v67
	v_rcp_f32_e32 v74, v67
	v_add_f32_e32 v67, 1.0, v69
	v_exp_f32_e32 v69, v102
	v_exp_f32_e32 v71, v103
	v_rcp_f32_e32 v75, v67
	v_add_f32_e32 v67, 1.0, v69
	v_pk_mul_f32 v[120:121], v[104:105], v[76:77]
	v_rcp_f32_e32 v76, v67
	v_add_f32_e32 v67, 1.0, v71
	v_rcp_f32_e32 v77, v67
	v_exp_f32_e32 v67, v108
	v_exp_f32_e32 v69, v109
	v_pk_mul_f32 v[122:123], v[98:99], v[74:75]
	v_add_f32_e32 v67, 1.0, v67
	v_rcp_f32_e32 v74, v67
	v_add_f32_e32 v67, 1.0, v69
	v_exp_f32_e32 v69, v106
	v_exp_f32_e32 v71, v107
	v_rcp_f32_e32 v75, v67
	v_add_f32_e32 v67, 1.0, v69
	v_rcp_f32_e32 v78, v67
	v_add_f32_e32 v67, 1.0, v71
	v_exp_f32_e32 v69, v116
	v_exp_f32_e32 v71, v117
	v_rcp_f32_e32 v79, v67
	v_add_f32_e32 v67, 1.0, v69
	v_rcp_f32_e32 v124, v67
	v_add_f32_e32 v67, 1.0, v71
	v_exp_f32_e32 v69, v114
	v_exp_f32_e32 v71, v115
	v_rcp_f32_e32 v125, v67
	v_add_f32_e32 v67, 1.0, v69
	v_rcp_f32_e32 v126, v67
	v_add_f32_e32 v67, 1.0, v71
	v_rcp_f32_e32 v127, v67
	v_pk_mul_f32 v[148:149], v[102:103], v[76:77]
	v_pk_mul_f32 v[150:151], v[108:109], v[74:75]
	v_pk_mul_f32 v[154:155], v[106:107], v[78:79]
	ds_read_b128 v[98:101], v195 offset:128
	ds_read_b128 v[102:105], v195 offset:384
	ds_read_b128 v[106:109], v195 offset:640
	ds_read_b128 v[110:113], v195 offset:896
	v_pk_mul_f32 v[90:91], v[44:45], v[88:89] op_sel_hi:[1,0]
	v_pk_mul_f32 v[78:79], v[32:33], v[82:83] op_sel_hi:[1,0]
	v_pk_mul_f32 v[94:95], v[36:37], v[84:85] op_sel_hi:[1,0]
	v_pk_mul_f32 v[74:75], v[40:41], v[86:87] op_sel_hi:[1,0]
	v_mov_b32_dpp v32, v78 row_shr:1 row_mask:0xf bank_mask:0xf bound_ctrl:1
	v_mov_b32_dpp v33, v79 row_shr:1 row_mask:0xf bank_mask:0xf bound_ctrl:1
	s_waitcnt lgkmcnt(0)
	v_pk_fma_f32 v[44:45], v[90:91], v[106:107], v[110:111]
	v_pk_mul_f32 v[80:81], v[34:35], v[82:83] op_sel_hi:[1,0]
	v_mov_b32_dpp v34, v94 row_shr:1 row_mask:0xf bank_mask:0xf bound_ctrl:1
	v_mov_b32_dpp v35, v95 row_shr:1 row_mask:0xf bank_mask:0xf bound_ctrl:1
	v_pk_fma_f32 v[44:45], v[102:103], v[32:33], v[44:45]
	v_pk_mul_f32 v[92:93], v[46:47], v[88:89] op_sel_hi:[1,0]
	v_pk_fma_f32 v[34:35], v[98:99], v[34:35], v[44:45]
	v_pk_fma_f32 v[44:45], v[74:75], v[106:107], v[110:111]
	v_pk_mul_f32 v[96:97], v[38:39], v[84:85] op_sel_hi:[1,0]
	v_mov_b32_dpp v36, v80 row_shr:1 row_mask:0xf bank_mask:0xf bound_ctrl:1
	v_mov_b32_dpp v37, v81 row_shr:1 row_mask:0xf bank_mask:0xf bound_ctrl:1
	v_pk_fma_f32 v[46:47], v[92:93], v[108:109], v[112:113]
	v_pk_fma_f32 v[44:45], v[90:91], v[102:103], v[44:45]
	v_pk_mul_f32 v[76:77], v[42:43], v[86:87] op_sel_hi:[1,0]
	v_mov_b32_dpp v38, v96 row_shr:1 row_mask:0xf bank_mask:0xf bound_ctrl:1
	v_mov_b32_dpp v39, v97 row_shr:1 row_mask:0xf bank_mask:0xf bound_ctrl:1
	v_pk_fma_f32 v[46:47], v[104:105], v[36:37], v[46:47]
	v_pk_fma_f32 v[32:33], v[98:99], v[32:33], v[44:45]
	v_pk_fma_f32 v[44:45], v[94:95], v[106:107], v[110:111]
	v_pk_fma_f32 v[38:39], v[100:101], v[38:39], v[46:47]
	v_pk_fma_f32 v[46:47], v[76:77], v[108:109], v[112:113]
	v_pk_fma_f32 v[44:45], v[74:75], v[102:103], v[44:45]
	v_pk_fma_f32 v[46:47], v[92:93], v[104:105], v[46:47]
	v_pk_fma_f32 v[44:45], v[90:91], v[98:99], v[44:45]
	v_pk_mul_f32 v[42:43], v[114:115], v[126:127]
	v_pk_fma_f32 v[36:37], v[100:101], v[36:37], v[46:47]
	v_pk_fma_f32 v[46:47], v[96:97], v[108:109], v[112:113]
	v_pk_mul_f32 v[114:115], v[44:45], v[150:151]
	v_pk_fma_f32 v[44:45], v[78:79], v[106:107], v[110:111]
	v_pk_fma_f32 v[106:107], v[80:81], v[108:109], v[112:113]
	v_pk_fma_f32 v[46:47], v[76:77], v[104:105], v[46:47]
	v_pk_fma_f32 v[104:105], v[96:97], v[104:105], v[106:107]
	v_pk_fma_f32 v[44:45], v[94:95], v[102:103], v[44:45]
	v_pk_mul_f32 v[40:41], v[116:117], v[124:125]
	v_pk_fma_f32 v[46:47], v[92:93], v[100:101], v[46:47]
	v_pk_fma_f32 v[44:45], v[74:75], v[98:99], v[44:45]
	v_pk_fma_f32 v[98:99], v[76:77], v[100:101], v[104:105]
	v_pk_mul_f32 v[38:39], v[120:121], v[38:39]
	v_pk_mul_f32 v[34:35], v[118:119], v[34:35]
	v_pk_mul_f32 v[36:37], v[148:149], v[36:37]
	v_pk_mul_f32 v[32:33], v[122:123], v[32:33]
	v_pk_mul_f32 v[46:47], v[46:47], v[154:155]
	v_pk_mul_f32 v[42:43], v[98:99], v[42:43]
	v_pk_mul_f32 v[98:99], v[44:45], v[40:41]
	v_cvt_pk_bf16_f32 v44, v34, v35
	v_cvt_pk_bf16_f32 v45, v38, v39
	v_cvt_pk_bf16_f32 v40, v32, v33
	v_cvt_pk_bf16_f32 v41, v36, v37
	v_cvt_pk_bf16_f32 v36, v114, v115
	v_cvt_pk_bf16_f32 v37, v46, v47
	s_nop 0
	v_cvt_pk_bf16_f32 v32, v98, v99
	v_cvt_pk_bf16_f32 v33, v42, v43
	ds_read_b128 v[102:105], v195 offset:16
	ds_read_b128 v[106:109], v195 offset:272
	ds_read_b128 v[110:113], v195 offset:528
	ds_read_b128 v[114:117], v195 offset:784
	v_pk_mul_f32 v[98:99], v[16:17], v[88:89] op_sel_hi:[1,0]
	v_pk_mul_f32 v[16:17], v[20:21], v[86:87] op_sel_hi:[1,0]
	v_pk_mul_f32 v[20:21], v[28:29], v[82:83] op_sel_hi:[1,0]
	v_pk_mul_f32 v[24:25], v[24:25], v[84:85] op_sel_hi:[1,0]
	s_waitcnt lgkmcnt(0)
; #define PG8_LAS __attribute__((address_space(3)))
;     __device__ __forceinline__ void operator()(f32x4 (&acc)[2][2][4][2], const pg8::Unit& u, int wr, int wc, int fr, int fq) const {
;     ...
;             for (int n = 0; n < 2; ++n) {
;                 f32x4 g[4];
;                 {   const PG8_LAS unsigned char* wq = wl + (8 * fq + 4 * n) * 4;
;                     const f32x4 w0 = *(const PG8_LAS f32x4*)(wq), w1 = *(const PG8_LAS f32x4*)(wq + 256), w2 = *(const PG8_LAS f32x4*)(wq + 512), bb = *(const PG8_LAS f32x4*)(wq + 768);
;                     const f32x4 x0 = acc[ai][0][0][n] * rstd[0], x1 = acc[ai][0][1][n] * rstd[1], x2 = acc[ai][0][2][n] * rstd[2], x3 = acc[ai][0][3][n] * rstd[3];
;                     acc[ai][0][0][n] = x0; acc[ai][0][1][n] = x1; acc[ai][0][2][n] = x2; acc[ai][0][3][n] = x3;
;                     f32x4 p1, p2;
; #pragma unroll
;                     for (int c = 0; c < 4; ++c) { p1[c] = row_up1(x3[c]); p2[c] = row_up1(x2[c]); }
;                     g[0] = bb + w2 * x0 + w1 * p1 + w0 * p2; g[1] = bb + w2 * x1 + w1 * x0 + w0 * p1;
;                     g[2] = bb + w2 * x2 + w1 * x1 + w0 * x0; g[3] = bb + w2 * x3 + w1 * x2 + w0 * x1;
; #pragma unroll
;                     for (int m = 0; m < 4; ++m)
; #pragma unroll
;                         for (int c = 0; c < 4; ++c) g[m][c] = siluf_(g[m][c]);
;                 }
;                 __builtin_amdgcn_sched_barrier(0);
;                 {   const PG8_LAS unsigned char* wq = wl + 128 + (8 * fq + 4 * n) * 4;
;                     const f32x4 w0 = *(const PG8_LAS f32x4*)(wq), w1 = *(const PG8_LAS f32x4*)(wq + 256), w2 = *(const PG8_LAS f32x4*)(wq + 512), bb = *(const PG8_LAS f32x4*)(wq + 768);
;                     const f32x4 x0 = acc[ai][1][0][n] * rstd[0], x1 = acc[ai][1][1][n] * rstd[1], x2 = acc[ai][1][2][n] * rstd[2], x3 = acc[ai][1][3][n] * rstd[3];
;                     acc[ai][1][0][n] = x0; acc[ai][1][1][n] = x1; acc[ai][1][2][n] = x2; acc[ai][1][3][n] = x3;
;                     f32x4 p1, p2;
; #pragma unroll
;                     for (int c = 0; c < 4; ++c) { p1[c] = row_up1(x3[c]); p2[c] = row_up1(x2[c]); }
;                     g[0] *= bb + w2 * x0 + w1 * p1 + w0 * p2; g[1] *= bb + w2 * x1 + w1 * x0 + w0 * p1;
;                     g[2] *= bb + w2 * x2 + w1 * x1 + w0 * x0; g[3] *= bb + w2 * x3 + w1 * x2 + w0 * x1;
;                 }
; #pragma unroll
	v_pk_fma_f32 v[46:47], v[98:99], v[110:111], v[114:115]
	v_mov_b32_dpp v28, v20 row_shr:1 row_mask:0xf bank_mask:0xf bound_ctrl:1
	v_mov_b32_dpp v29, v21 row_shr:1 row_mask:0xf bank_mask:0xf bound_ctrl:1
	v_pk_mul_f32 v[100:101], v[18:19], v[88:89] op_sel_hi:[1,0]
	v_pk_mul_f32 v[18:19], v[22:23], v[86:87] op_sel_hi:[1,0]
	v_pk_mul_f32 v[22:23], v[30:31], v[82:83] op_sel_hi:[1,0]
	v_mov_b32_dpp v30, v24 row_shr:1 row_mask:0xf bank_mask:0xf bound_ctrl:1
	v_mov_b32_dpp v31, v25 row_shr:1 row_mask:0xf bank_mask:0xf bound_ctrl:1
	v_pk_fma_f32 v[46:47], v[106:107], v[28:29], v[46:47]
	v_pk_mul_f32 v[26:27], v[26:27], v[84:85] op_sel_hi:[1,0]
	v_pk_fma_f32 v[30:31], v[102:103], v[30:31], v[46:47]
	v_pk_fma_f32 v[46:47], v[16:17], v[110:111], v[114:115]
	v_exp_f32_e32 v67, v30
	v_exp_f32_e32 v69, v31
	v_mov_b32_dpp v34, v22 row_shr:1 row_mask:0xf bank_mask:0xf bound_ctrl:1
	v_mov_b32_dpp v35, v23 row_shr:1 row_mask:0xf bank_mask:0xf bound_ctrl:1
	v_pk_fma_f32 v[42:43], v[100:101], v[112:113], v[116:117]
	v_pk_fma_f32 v[46:47], v[98:99], v[106:107], v[46:47]
	v_mov_b32_dpp v38, v26 row_shr:1 row_mask:0xf bank_mask:0xf bound_ctrl:1
	v_mov_b32_dpp v39, v27 row_shr:1 row_mask:0xf bank_mask:0xf bound_ctrl:1
	v_pk_fma_f32 v[42:43], v[108:109], v[34:35], v[42:43]
	v_pk_fma_f32 v[28:29], v[102:103], v[28:29], v[46:47]
	v_pk_fma_f32 v[46:47], v[24:25], v[110:111], v[114:115]
	v_pk_fma_f32 v[110:111], v[20:21], v[110:111], v[114:115]
	v_pk_fma_f32 v[38:39], v[104:105], v[38:39], v[42:43]
	v_pk_fma_f32 v[46:47], v[16:17], v[106:107], v[46:47]
	v_pk_fma_f32 v[106:107], v[24:25], v[106:107], v[110:111]
	v_add_f32_e32 v67, 1.0, v67
	v_pk_fma_f32 v[46:47], v[98:99], v[102:103], v[46:47]
	v_pk_fma_f32 v[120:121], v[16:17], v[102:103], v[106:107]
	v_rcp_f32_e32 v102, v67
	v_add_f32_e32 v67, 1.0, v69
	v_exp_f32_e32 v69, v38
	v_pk_fma_f32 v[42:43], v[18:19], v[112:113], v[116:117]
	v_exp_f32_e32 v71, v39
	v_pk_fma_f32 v[42:43], v[100:101], v[108:109], v[42:43]
	v_rcp_f32_e32 v103, v67
	v_pk_fma_f32 v[34:35], v[104:105], v[34:35], v[42:43]
	v_pk_fma_f32 v[42:43], v[26:27], v[112:113], v[116:117]
	v_pk_fma_f32 v[112:113], v[22:23], v[112:113], v[116:117]
	v_pk_fma_f32 v[42:43], v[18:19], v[108:109], v[42:43]
	v_pk_fma_f32 v[108:109], v[26:27], v[108:109], v[112:113]
	v_add_f32_e32 v67, 1.0, v69
	v_pk_fma_f32 v[42:43], v[100:101], v[104:105], v[42:43]
	v_pk_fma_f32 v[118:119], v[18:19], v[104:105], v[108:109]
	v_rcp_f32_e32 v104, v67
	v_add_f32_e32 v67, 1.0, v71
	v_rcp_f32_e32 v105, v67
	v_exp_f32_e32 v67, v34
	v_pk_mul_f32 v[122:123], v[30:31], v[102:103]
	v_exp_f32_e32 v69, v35
	v_exp_f32_e32 v30, v28
	v_exp_f32_e32 v31, v29
	v_add_f32_e32 v67, 1.0, v67
	v_rcp_f32_e32 v102, v67
	v_add_f32_e32 v67, 1.0, v69
	v_add_f32_e32 v30, 1.0, v30
	v_add_f32_e32 v31, 1.0, v31
	v_rcp_f32_e32 v103, v67
	v_rcp_f32_e32 v30, v30
	v_rcp_f32_e32 v31, v31
	v_exp_f32_e32 v67, v46
	v_exp_f32_e32 v69, v47
	v_pk_mul_f32 v[124:125], v[28:29], v[30:31]
	v_add_f32_e32 v28, 1.0, v67
	v_add_f32_e32 v29, 1.0, v69
	v_exp_f32_e32 v67, v120
	v_exp_f32_e32 v69, v121
	v_exp_f32_e32 v30, v42
	v_exp_f32_e32 v31, v43
	v_add_f32_e32 v67, 1.0, v67
	v_rcp_f32_e32 v126, v67
	v_add_f32_e32 v67, 1.0, v69
	v_add_f32_e32 v30, 1.0, v30
	v_add_f32_e32 v31, 1.0, v31
	v_exp_f32_e32 v69, v118
	v_rcp_f32_e32 v28, v28
	v_rcp_f32_e32 v29, v29
	v_rcp_f32_e32 v30, v30
	v_rcp_f32_e32 v31, v31
	v_exp_f32_e32 v71, v119
	v_rcp_f32_e32 v127, v67
	v_add_f32_e32 v67, 1.0, v69
	v_pk_mul_f32 v[38:39], v[38:39], v[104:105]
	v_rcp_f32_e32 v148, v67
	v_add_f32_e32 v67, 1.0, v71
	v_pk_mul_f32 v[34:35], v[34:35], v[102:103]
	v_pk_mul_f32 v[46:47], v[46:47], v[28:29]
	v_pk_mul_f32 v[42:43], v[42:43], v[30:31]
	v_rcp_f32_e32 v149, v67
	ds_read_b128 v[102:105], v195 offset:144
	ds_read_b128 v[106:109], v195 offset:400
	ds_read_b128 v[110:113], v195 offset:656
	ds_read_b128 v[114:117], v195 offset:912
	v_pk_mul_f32 v[30:31], v[2:3], v[88:89] op_sel_hi:[1,0]
	v_pk_mul_f32 v[28:29], v[0:1], v[88:89] op_sel_hi:[1,0]
	v_pk_mul_f32 v[2:3], v[6:7], v[86:87] op_sel_hi:[1,0]
	v_pk_mul_f32 v[0:1], v[4:5], v[86:87] op_sel_hi:[1,0]
	v_pk_mul_f32 v[6:7], v[14:15], v[82:83] op_sel_hi:[1,0]
	v_pk_mul_f32 v[4:5], v[12:13], v[82:83] op_sel_hi:[1,0]
	v_pk_mul_f32 v[10:11], v[10:11], v[84:85] op_sel_hi:[1,0]
	v_pk_mul_f32 v[8:9], v[8:9], v[84:85] op_sel_hi:[1,0]
	v_mov_b32_dpp v12, v4 row_shr:1 row_mask:0xf bank_mask:0xf bound_ctrl:1
	v_mov_b32_dpp v13, v5 row_shr:1 row_mask:0xf bank_mask:0xf bound_ctrl:1
	v_mov_b32_dpp v82, v6 row_shr:1 row_mask:0xf bank_mask:0xf bound_ctrl:1
	v_mov_b32_dpp v83, v7 row_shr:1 row_mask:0xf bank_mask:0xf bound_ctrl:1
	v_pk_mul_f32 v[86:87], v[120:121], v[126:127]
	v_pk_mul_f32 v[88:89], v[118:119], v[148:149]
	s_waitcnt lgkmcnt(0)
; __device__ __forceinline__ unsigned pk2(float a, float b) { return pg8::cvt_pk_bf16(a, b); }
;     __device__ __forceinline__ void operator()(f32x4 (&acc)[2][2][4][2], const pg8::Unit& u, int wr, int wc, int fr, int fq) const {
;     ...
;                     g[0] *= bb + w2 * x0 + w1 * p1 + w0 * p2; g[1] *= bb + w2 * x1 + w1 * x0 + w0 * p1;
;                     g[2] *= bb + w2 * x2 + w1 * x1 + w0 * x0; g[3] *= bb + w2 * x3 + w1 * x2 + w0 * x1;
;                 }
; #pragma unroll
;                 for (int m = 0; m < 4; ++m) { pk[n][m].x = pk2(g[m][0], g[m][1]); pk[n][m].y = pk2(g[m][2], g[m][3]); }
;                 __builtin_amdgcn_sched_barrier(0);
;             }
; #pragma unroll
;             for (int m = 0; m < 4; ++m) if (fr != 0 || m >= 2) {
;                 u32x4 w; w.x = pk[0][m].x; w.y = pk[0][m].y; w.z = pk[1][m].x; w.w = pk[1][m].y;
;                 *(u32x4*)(ACT + (size_t)(tb + m) * DFF + colj) = w; }
	v_pk_fma_f32 v[118:119], v[28:29], v[110:111], v[114:115]
	v_pk_fma_f32 v[120:121], v[30:31], v[112:113], v[116:117]
	v_mov_b32_dpp v14, v8 row_shr:1 row_mask:0xf bank_mask:0xf bound_ctrl:1
	v_mov_b32_dpp v15, v9 row_shr:1 row_mask:0xf bank_mask:0xf bound_ctrl:1
	v_mov_b32_dpp v84, v10 row_shr:1 row_mask:0xf bank_mask:0xf bound_ctrl:1
	v_mov_b32_dpp v85, v11 row_shr:1 row_mask:0xf bank_mask:0xf bound_ctrl:1
	v_pk_fma_f32 v[120:121], v[108:109], v[82:83], v[120:121]
	v_pk_fma_f32 v[118:119], v[106:107], v[12:13], v[118:119]
	v_pk_fma_f32 v[84:85], v[104:105], v[84:85], v[120:121]
	v_pk_fma_f32 v[14:15], v[102:103], v[14:15], v[118:119]
	v_pk_fma_f32 v[118:119], v[2:3], v[112:113], v[116:117]
	v_pk_mul_f32 v[38:39], v[38:39], v[84:85]
	v_pk_fma_f32 v[84:85], v[0:1], v[110:111], v[114:115]
	v_pk_fma_f32 v[118:119], v[30:31], v[108:109], v[118:119]
	v_pk_fma_f32 v[84:85], v[28:29], v[106:107], v[84:85]
	v_pk_fma_f32 v[82:83], v[104:105], v[82:83], v[118:119]
	v_pk_fma_f32 v[12:13], v[102:103], v[12:13], v[84:85]
	v_pk_mul_f32 v[34:35], v[34:35], v[82:83]
	v_pk_fma_f32 v[82:83], v[8:9], v[110:111], v[114:115]
	v_pk_fma_f32 v[84:85], v[10:11], v[112:113], v[116:117]
	v_pk_fma_f32 v[82:83], v[0:1], v[106:107], v[82:83]
	v_pk_fma_f32 v[84:85], v[2:3], v[108:109], v[84:85]
	v_pk_fma_f32 v[82:83], v[28:29], v[102:103], v[82:83]
	v_pk_fma_f32 v[84:85], v[30:31], v[104:105], v[84:85]
	v_pk_mul_f32 v[82:83], v[46:47], v[82:83]
	v_pk_mul_f32 v[84:85], v[42:43], v[84:85]
	v_pk_fma_f32 v[42:43], v[4:5], v[110:111], v[114:115]
	v_pk_fma_f32 v[46:47], v[6:7], v[112:113], v[116:117]
	v_pk_fma_f32 v[42:43], v[8:9], v[106:107], v[42:43]
	v_pk_fma_f32 v[46:47], v[10:11], v[108:109], v[46:47]
	v_pk_fma_f32 v[42:43], v[0:1], v[102:103], v[42:43]
	v_pk_fma_f32 v[46:47], v[2:3], v[104:105], v[46:47]
	v_pk_mul_f32 v[14:15], v[122:123], v[14:15]
	v_pk_mul_f32 v[12:13], v[124:125], v[12:13]
	v_pk_mul_f32 v[88:89], v[88:89], v[46:47]
	v_pk_mul_f32 v[86:87], v[86:87], v[42:43]
	v_cvt_pk_bf16_f32 v46, v14, v15
	v_cvt_pk_bf16_f32 v47, v38, v39
	v_cvt_pk_bf16_f32 v42, v12, v13
	v_cvt_pk_bf16_f32 v43, v34, v35
	v_cvt_pk_bf16_f32 v38, v82, v83
	v_cvt_pk_bf16_f32 v39, v84, v85
	s_nop 0
	v_cvt_pk_bf16_f32 v34, v86, v87
	v_cvt_pk_bf16_f32 v35, v88, v89
	s_and_saveexec_b64 s[8:9], s[0:1]
	s_cbranch_execz .LBB0_756
	v_mov_b64_e32 v[12:13], s[22:23]
	v_mad_i64_i32 v[14:15], s[10:11], v66, s56, v[12:13]
	v_mad_i64_i32 v[12:13], s[10:11], v68, s56, v[12:13]
	v_lshl_add_u64 v[14:15], v[14:15], 0, v[64:65]
	v_lshl_add_u64 v[12:13], v[12:13], 0, v[64:65]
	global_store_dwordx4 v[14:15], v[44:47], off
	global_store_dwordx4 v[12:13], v[40:43], off
